# GEMM K-loops: LDS-DMA pieces per super-phase 3,5,3,5 (last piece of super-phase 3 requested at the top of the next iteration); vmcnt(7) behind the 5-piece super-phases
# speedup vs baseline: 1.0153x; 1.0024x over previous
.LBB0_367:
	s_cmp_eq_u32 s65, -2
	s_cbranch_scc1 .Lcar_367
	s_mov_b32 m0, s57
	s_nop 0
	global_load_lds_dwordx4 v150, s[70:71]
.Lcar_367:
	ds_read_b128 v[130:133], v168
	ds_read_b128 v[134:137], v168 offset:1024
	ds_read_b128 v[138:141], v168 offset:2048
	ds_read_b128 v[142:145], v168 offset:3072
	ds_read_b128 v[172:175], v169
	ds_read_b128 v[176:179], v169 offset:1024
	ds_read_b128 v[180:183], v169 offset:2048
	ds_read_b128 v[184:187], v169 offset:3072
	s_add_u32 s36, s34, 0xfffc0080
	s_addc_u32 s37, s35, -1
	s_cmp_eq_u32 s65, 12
	s_cselect_b32 s39, s1, s37
	s_cselect_b32 s38, s25, s36
	s_cselect_b32 s37, s23, s41
	s_cselect_b32 s36, s31, s40
	s_add_u32 s70, s38, 0x80
	s_addc_u32 s71, s39, 0
	s_add_i32 m0, s47, 0xc000
	ds_read_b128 v[188:191], v170
	ds_read_b128 v[192:195], v170 offset:1024
	ds_read_b128 v[196:199], v170 offset:2048
	ds_read_b128 v[200:203], v170 offset:3072
	ds_read_b128 v[204:207], v170 offset:4096
	ds_read_b128 v[208:211], v170 offset:5120
	ds_read_b128 v[212:215], v170 offset:6144
	ds_read_b128 v[216:219], v170 offset:7168
	global_load_lds_dwordx4 v158, s[34:35]
	s_add_i32 m0, s47, 0xe000
	s_nop 0
	global_load_lds_dwordx4 v160, s[34:35]
	s_waitcnt vmcnt(8)
	s_waitcnt lgkmcnt(0)
	s_barrier
	s_setprio 1
	s_waitcnt lgkmcnt(0)
	v_mfma_f32_16x16x32_bf16 v[126:129], v[130:133], v[188:191], v[126:129]
	v_mfma_f32_16x16x32_bf16 v[122:125], v[138:141], v[188:191], v[122:125]
	v_mfma_f32_16x16x32_bf16 v[110:113], v[130:133], v[196:199], v[110:113]
	v_mfma_f32_16x16x32_bf16 v[106:109], v[138:141], v[196:199], v[106:109]
	v_mfma_f32_16x16x32_bf16 v[94:97], v[130:133], v[204:207], v[94:97]
	v_mfma_f32_16x16x32_bf16 v[90:93], v[138:141], v[204:207], v[90:93]
	v_mfma_f32_16x16x32_bf16 v[78:81], v[130:133], v[212:215], v[78:81]
	v_mfma_f32_16x16x32_bf16 v[74:77], v[138:141], v[212:215], v[74:77]
	v_mfma_f32_16x16x32_bf16 v[126:129], v[134:137], v[192:195], v[126:129]
	v_mfma_f32_16x16x32_bf16 v[122:125], v[142:145], v[192:195], v[122:125]
	v_mfma_f32_16x16x32_bf16 v[110:113], v[134:137], v[200:203], v[110:113]
	v_mfma_f32_16x16x32_bf16 v[106:109], v[142:145], v[200:203], v[106:109]
	v_mfma_f32_16x16x32_bf16 v[94:97], v[134:137], v[208:211], v[94:97]
	v_mfma_f32_16x16x32_bf16 v[90:93], v[142:145], v[208:211], v[90:93]
	v_mfma_f32_16x16x32_bf16 v[78:81], v[134:137], v[216:219], v[78:81]
	v_mfma_f32_16x16x32_bf16 v[74:77], v[142:145], v[216:219], v[74:77]
	s_setprio 0
	s_setprio 1
	v_mfma_f32_16x16x32_bf16 v[118:121], v[172:175], v[188:191], v[118:121]
	v_mfma_f32_16x16x32_bf16 v[114:117], v[180:183], v[188:191], v[114:117]
	v_mfma_f32_16x16x32_bf16 v[102:105], v[172:175], v[196:199], v[102:105]
	v_mfma_f32_16x16x32_bf16 v[98:101], v[180:183], v[196:199], v[98:101]
	v_mfma_f32_16x16x32_bf16 v[86:89], v[172:175], v[204:207], v[86:89]
	v_mfma_f32_16x16x32_bf16 v[82:85], v[180:183], v[204:207], v[82:85]
	v_mfma_f32_16x16x32_bf16 v[70:73], v[172:175], v[212:215], v[70:73]
	v_mfma_f32_16x16x32_bf16 v[66:69], v[180:183], v[212:215], v[66:69]
	v_mfma_f32_16x16x32_bf16 v[118:121], v[176:179], v[192:195], v[118:121]
	v_mfma_f32_16x16x32_bf16 v[114:117], v[184:187], v[192:195], v[114:117]
	v_mfma_f32_16x16x32_bf16 v[102:105], v[176:179], v[200:203], v[102:105]
	v_mfma_f32_16x16x32_bf16 v[98:101], v[184:187], v[200:203], v[98:101]
	v_mfma_f32_16x16x32_bf16 v[86:89], v[176:179], v[208:211], v[86:89]
	v_mfma_f32_16x16x32_bf16 v[82:85], v[184:187], v[208:211], v[82:85]
	v_mfma_f32_16x16x32_bf16 v[70:73], v[176:179], v[216:219], v[70:73]
	v_mfma_f32_16x16x32_bf16 v[66:69], v[184:187], v[216:219], v[66:69]
	s_setprio 0
	s_barrier
	s_add_i32 s66, s61, s46
	s_mov_b32 m0, s66
	ds_read_b128 v[188:191], v170 offset:16384
	ds_read_b128 v[192:195], v170 offset:17408
	ds_read_b128 v[196:199], v170 offset:18432
	ds_read_b128 v[200:203], v170 offset:19456
	ds_read_b128 v[204:207], v170 offset:20480
	ds_read_b128 v[208:211], v170 offset:21504
	ds_read_b128 v[212:215], v170 offset:22528
	ds_read_b128 v[216:219], v170 offset:23552
	global_load_lds_dwordx4 v148, s[36:37]
	s_add_i32 m0, s66, 0x2000
	s_add_u32 s66, s36, 0x10000
	s_addc_u32 s67, s37, 0
	s_add_i32 s68, s62, s46
	global_load_lds_dwordx4 v152, s[36:37]
	s_mov_b32 m0, s68
	s_nop 0
	global_load_lds_dwordx4 v148, s[66:67]
	s_add_i32 m0, s68, 0x2000
	s_nop 0
	global_load_lds_dwordx4 v152, s[66:67]
	s_mov_b32 m0, s47
	s_nop 0
	global_load_lds_dwordx4 v146, s[38:39]
	s_waitcnt vmcnt(7)
	s_waitcnt lgkmcnt(0)
	s_barrier
	s_setprio 1
	s_waitcnt lgkmcnt(0)
	v_mfma_f32_16x16x32_bf16 v[62:65], v[130:133], v[188:191], v[62:65]
	v_mfma_f32_16x16x32_bf16 v[58:61], v[138:141], v[188:191], v[58:61]
	v_mfma_f32_16x16x32_bf16 v[46:49], v[130:133], v[196:199], v[46:49]
	v_mfma_f32_16x16x32_bf16 v[42:45], v[138:141], v[196:199], v[42:45]
	v_mfma_f32_16x16x32_bf16 v[30:33], v[130:133], v[204:207], v[30:33]
	v_mfma_f32_16x16x32_bf16 v[26:29], v[138:141], v[204:207], v[26:29]
	v_mfma_f32_16x16x32_bf16 v[14:17], v[130:133], v[212:215], v[14:17]
	v_mfma_f32_16x16x32_bf16 v[10:13], v[138:141], v[212:215], v[10:13]
	v_mfma_f32_16x16x32_bf16 v[62:65], v[134:137], v[192:195], v[62:65]
	v_mfma_f32_16x16x32_bf16 v[58:61], v[142:145], v[192:195], v[58:61]
	v_mfma_f32_16x16x32_bf16 v[46:49], v[134:137], v[200:203], v[46:49]
	v_mfma_f32_16x16x32_bf16 v[42:45], v[142:145], v[200:203], v[42:45]
	v_mfma_f32_16x16x32_bf16 v[30:33], v[134:137], v[208:211], v[30:33]
	v_mfma_f32_16x16x32_bf16 v[26:29], v[142:145], v[208:211], v[26:29]
	v_mfma_f32_16x16x32_bf16 v[14:17], v[134:137], v[216:219], v[14:17]
	v_mfma_f32_16x16x32_bf16 v[10:13], v[142:145], v[216:219], v[10:13]
	s_setprio 0
	s_setprio 1
	v_mfma_f32_16x16x32_bf16 v[54:57], v[172:175], v[188:191], v[54:57]
	v_mfma_f32_16x16x32_bf16 v[50:53], v[180:183], v[188:191], v[50:53]
	v_mfma_f32_16x16x32_bf16 v[38:41], v[172:175], v[196:199], v[38:41]
	v_mfma_f32_16x16x32_bf16 v[34:37], v[180:183], v[196:199], v[34:37]
	v_mfma_f32_16x16x32_bf16 v[22:25], v[172:175], v[204:207], v[22:25]
	v_mfma_f32_16x16x32_bf16 v[18:21], v[180:183], v[204:207], v[18:21]
	v_mfma_f32_16x16x32_bf16 v[6:9], v[172:175], v[212:215], v[6:9]
	v_mfma_f32_16x16x32_bf16 v[2:5], v[180:183], v[212:215], v[2:5]
	v_mfma_f32_16x16x32_bf16 v[54:57], v[176:179], v[192:195], v[54:57]
	v_mfma_f32_16x16x32_bf16 v[50:53], v[184:187], v[192:195], v[50:53]
	v_mfma_f32_16x16x32_bf16 v[38:41], v[176:179], v[200:203], v[38:41]
	v_mfma_f32_16x16x32_bf16 v[34:37], v[184:187], v[200:203], v[34:37]
	v_mfma_f32_16x16x32_bf16 v[22:25], v[176:179], v[208:211], v[22:25]
	v_mfma_f32_16x16x32_bf16 v[18:21], v[184:187], v[208:211], v[18:21]
	v_mfma_f32_16x16x32_bf16 v[6:9], v[176:179], v[216:219], v[6:9]
	v_mfma_f32_16x16x32_bf16 v[2:5], v[184:187], v[216:219], v[2:5]
	s_setprio 0
	s_barrier
	s_add_i32 s66, 0, 0x18000
	s_add_i32 s67, 0, 0x1c000
	v_add_u32_e32 v142, s66, v157
	v_add_u32_e32 v154, s67, v157
	ds_read_b128 v[130:133], v142
	ds_read_b128 v[134:137], v142 offset:1024
	ds_read_b128 v[138:141], v142 offset:2048
	ds_read_b128 v[142:145], v142 offset:3072
	ds_read_b128 v[172:175], v154
	ds_read_b128 v[176:179], v154 offset:1024
	ds_read_b128 v[180:183], v154 offset:2048
	ds_read_b128 v[184:187], v154 offset:3072
	s_mov_b32 m0, s48
	s_nop 0
	global_load_lds_dwordx4 v150, s[38:39]
	s_add_u32 s38, s38, 0x40000
	s_addc_u32 s39, s39, 0
	s_mov_b32 m0, s49
	ds_read_b128 v[188:191], v170 offset:32768
	ds_read_b128 v[192:195], v170 offset:33792
	ds_read_b128 v[196:199], v170 offset:34816
	ds_read_b128 v[200:203], v170 offset:35840
	ds_read_b128 v[204:207], v170 offset:36864
	ds_read_b128 v[208:211], v170 offset:37888
	ds_read_b128 v[212:215], v170 offset:38912
	ds_read_b128 v[216:219], v170 offset:39936
	global_load_lds_dwordx4 v146, s[38:39]
	s_mov_b32 m0, s50
	s_nop 0
	global_load_lds_dwordx4 v150, s[38:39]
	s_waitcnt vmcnt(8)
	s_waitcnt lgkmcnt(0)
	s_barrier
	s_setprio 1
	s_waitcnt lgkmcnt(0)
	v_mfma_f32_16x16x32_bf16 v[126:129], v[130:133], v[188:191], v[126:129]
	v_mfma_f32_16x16x32_bf16 v[122:125], v[138:141], v[188:191], v[122:125]
	v_mfma_f32_16x16x32_bf16 v[110:113], v[130:133], v[196:199], v[110:113]
	v_mfma_f32_16x16x32_bf16 v[106:109], v[138:141], v[196:199], v[106:109]
	v_mfma_f32_16x16x32_bf16 v[94:97], v[130:133], v[204:207], v[94:97]
	v_mfma_f32_16x16x32_bf16 v[90:93], v[138:141], v[204:207], v[90:93]
	v_mfma_f32_16x16x32_bf16 v[78:81], v[130:133], v[212:215], v[78:81]
	v_mfma_f32_16x16x32_bf16 v[74:77], v[138:141], v[212:215], v[74:77]
	v_mfma_f32_16x16x32_bf16 v[126:129], v[134:137], v[192:195], v[126:129]
	v_mfma_f32_16x16x32_bf16 v[122:125], v[142:145], v[192:195], v[122:125]
	v_mfma_f32_16x16x32_bf16 v[110:113], v[134:137], v[200:203], v[110:113]
	v_mfma_f32_16x16x32_bf16 v[106:109], v[142:145], v[200:203], v[106:109]
	v_mfma_f32_16x16x32_bf16 v[94:97], v[134:137], v[208:211], v[94:97]
	v_mfma_f32_16x16x32_bf16 v[90:93], v[142:145], v[208:211], v[90:93]
	v_mfma_f32_16x16x32_bf16 v[78:81], v[134:137], v[216:219], v[78:81]
	v_mfma_f32_16x16x32_bf16 v[74:77], v[142:145], v[216:219], v[74:77]
	s_setprio 0
	s_setprio 1
	v_mfma_f32_16x16x32_bf16 v[118:121], v[172:175], v[188:191], v[118:121]
	v_mfma_f32_16x16x32_bf16 v[114:117], v[180:183], v[188:191], v[114:117]
	v_mfma_f32_16x16x32_bf16 v[102:105], v[172:175], v[196:199], v[102:105]
	v_mfma_f32_16x16x32_bf16 v[98:101], v[180:183], v[196:199], v[98:101]
	v_mfma_f32_16x16x32_bf16 v[86:89], v[172:175], v[204:207], v[86:89]
	v_mfma_f32_16x16x32_bf16 v[82:85], v[180:183], v[204:207], v[82:85]
	v_mfma_f32_16x16x32_bf16 v[70:73], v[172:175], v[212:215], v[70:73]
	v_mfma_f32_16x16x32_bf16 v[66:69], v[180:183], v[212:215], v[66:69]
	v_mfma_f32_16x16x32_bf16 v[118:121], v[176:179], v[192:195], v[118:121]
	v_mfma_f32_16x16x32_bf16 v[114:117], v[184:187], v[192:195], v[114:117]
	v_mfma_f32_16x16x32_bf16 v[102:105], v[176:179], v[200:203], v[102:105]
	v_mfma_f32_16x16x32_bf16 v[98:101], v[184:187], v[200:203], v[98:101]
	v_mfma_f32_16x16x32_bf16 v[86:89], v[176:179], v[208:211], v[86:89]
	v_mfma_f32_16x16x32_bf16 v[82:85], v[184:187], v[208:211], v[82:85]
	v_mfma_f32_16x16x32_bf16 v[70:73], v[176:179], v[216:219], v[70:73]
	v_mfma_f32_16x16x32_bf16 v[66:69], v[184:187], v[216:219], v[66:69]
	s_setprio 0
	s_barrier
	s_add_i32 s38, s66, s46
	s_mov_b32 m0, s38
	ds_read_b128 v[188:191], v170 offset:49152
	ds_read_b128 v[192:195], v170 offset:50176
	ds_read_b128 v[196:199], v170 offset:51200
	ds_read_b128 v[200:203], v170 offset:52224
	ds_read_b128 v[204:207], v170 offset:53248
	ds_read_b128 v[208:211], v170 offset:54272
	ds_read_b128 v[212:215], v170 offset:55296
	ds_read_b128 v[216:219], v170 offset:56320
	s_add_u32 s36, s36, 0x80
	s_addc_u32 s37, s37, 0
	global_load_lds_dwordx4 v148, s[36:37]
	s_add_i32 m0, s38, 0x2000
	s_add_i32 s38, s67, s46
	global_load_lds_dwordx4 v152, s[36:37]
	s_add_u32 s36, s36, 0x10000
	s_addc_u32 s37, s37, 0
	s_mov_b32 m0, s38
	s_nop 0
	global_load_lds_dwordx4 v148, s[36:37]
	s_add_i32 m0, s38, 0x2000
	s_nop 0
	global_load_lds_dwordx4 v152, s[36:37]
	s_mov_b32 m0, s56
	s_nop 0
	global_load_lds_dwordx4 v146, s[70:71]
	s_waitcnt vmcnt(7)
	s_waitcnt lgkmcnt(0)
	s_barrier
	s_setprio 1
	s_waitcnt lgkmcnt(0)
	v_mfma_f32_16x16x32_bf16 v[62:65], v[130:133], v[188:191], v[62:65]
	v_mfma_f32_16x16x32_bf16 v[58:61], v[138:141], v[188:191], v[58:61]
	v_mfma_f32_16x16x32_bf16 v[46:49], v[130:133], v[196:199], v[46:49]
	v_mfma_f32_16x16x32_bf16 v[42:45], v[138:141], v[196:199], v[42:45]
	v_mfma_f32_16x16x32_bf16 v[30:33], v[130:133], v[204:207], v[30:33]
	v_mfma_f32_16x16x32_bf16 v[26:29], v[138:141], v[204:207], v[26:29]
	v_mfma_f32_16x16x32_bf16 v[14:17], v[130:133], v[212:215], v[14:17]
	v_mfma_f32_16x16x32_bf16 v[10:13], v[138:141], v[212:215], v[10:13]
	v_mfma_f32_16x16x32_bf16 v[62:65], v[134:137], v[192:195], v[62:65]
	v_mfma_f32_16x16x32_bf16 v[58:61], v[142:145], v[192:195], v[58:61]
	v_mfma_f32_16x16x32_bf16 v[46:49], v[134:137], v[200:203], v[46:49]
	v_mfma_f32_16x16x32_bf16 v[42:45], v[142:145], v[200:203], v[42:45]
	v_mfma_f32_16x16x32_bf16 v[30:33], v[134:137], v[208:211], v[30:33]
	v_mfma_f32_16x16x32_bf16 v[26:29], v[142:145], v[208:211], v[26:29]
	v_mfma_f32_16x16x32_bf16 v[14:17], v[134:137], v[216:219], v[14:17]
	v_mfma_f32_16x16x32_bf16 v[10:13], v[142:145], v[216:219], v[10:13]
	s_setprio 0
	s_setprio 1
	v_mfma_f32_16x16x32_bf16 v[54:57], v[172:175], v[188:191], v[54:57]
	v_mfma_f32_16x16x32_bf16 v[50:53], v[180:183], v[188:191], v[50:53]
	v_mfma_f32_16x16x32_bf16 v[38:41], v[172:175], v[196:199], v[38:41]
	v_mfma_f32_16x16x32_bf16 v[34:37], v[180:183], v[196:199], v[34:37]
	v_mfma_f32_16x16x32_bf16 v[22:25], v[172:175], v[204:207], v[22:25]
	s_add_i32 s65, s65, 2
	v_mfma_f32_16x16x32_bf16 v[18:21], v[180:183], v[204:207], v[18:21]
	v_mfma_f32_16x16x32_bf16 v[6:9], v[172:175], v[212:215], v[6:9]
	s_add_u32 s34, s34, 0x100
	s_addc_u32 s35, s35, 0
	v_mfma_f32_16x16x32_bf16 v[2:5], v[180:183], v[212:215], v[2:5]
	v_mfma_f32_16x16x32_bf16 v[54:57], v[176:179], v[192:195], v[54:57]
	s_add_u32 s40, s40, 0x100
	s_addc_u32 s41, s41, 0
	v_mfma_f32_16x16x32_bf16 v[50:53], v[184:187], v[192:195], v[50:53]
	v_mfma_f32_16x16x32_bf16 v[38:41], v[176:179], v[200:203], v[38:41]
	s_cmp_gt_u32 s65, 13
	v_mfma_f32_16x16x32_bf16 v[34:37], v[184:187], v[200:203], v[34:37]
	v_mfma_f32_16x16x32_bf16 v[22:25], v[176:179], v[208:211], v[22:25]
	v_mfma_f32_16x16x32_bf16 v[18:21], v[184:187], v[208:211], v[18:21]
	v_mfma_f32_16x16x32_bf16 v[6:9], v[176:179], v[216:219], v[6:9]
	v_mfma_f32_16x16x32_bf16 v[2:5], v[184:187], v[216:219], v[2:5]
	s_setprio 0
	s_barrier
	s_cbranch_scc0 .LBB0_367
	s_mov_b32 m0, s57
	s_nop 0
	global_load_lds_dwordx4 v150, s[70:71]
	s_and_b64 vcc, exec, s[20:21]
	s_cbranch_vccz .LBB0_370
	s_barrier

.LBB0_766:
	s_cmp_eq_u32 s63, -2
	s_cbranch_scc1 .Lcar_766
	s_mov_b32 m0, s53
	s_nop 0
	global_load_lds_dwordx4 v146, s[68:69]
.Lcar_766:
	ds_read_b128 v[128:131], v163
	ds_read_b128 v[132:135], v163 offset:1024
	ds_read_b128 v[136:139], v163 offset:2048
	ds_read_b128 v[140:143], v163 offset:3072
	ds_read_b128 v[156:159], v164
	ds_read_b128 v[166:169], v164 offset:1024
	ds_read_b128 v[170:173], v164 offset:2048
	ds_read_b128 v[174:177], v164 offset:3072
	s_add_u32 s38, s36, 0xfffc0080
	s_addc_u32 s39, s37, -1
	s_cmp_eq_u32 s63, 12
	s_cselect_b32 s41, s27, s39
	s_cselect_b32 s40, s59, s38
	s_cselect_b32 s39, s25, s62
	s_cselect_b32 s38, s60, s61
	s_add_u32 s68, s40, 0x80
	s_addc_u32 s69, s41, 0
	s_add_i32 m0, s35, 0xc000
	ds_read_b128 v[178:181], v165
	ds_read_b128 v[182:185], v165 offset:1024
	ds_read_b128 v[186:189], v165 offset:2048
	ds_read_b128 v[190:193], v165 offset:3072
	ds_read_b128 v[194:197], v165 offset:4096
	ds_read_b128 v[198:201], v165 offset:5120
	ds_read_b128 v[202:205], v165 offset:6144
	ds_read_b128 v[206:209], v165 offset:7168
	global_load_lds_dwordx4 v148, s[36:37]
	s_add_i32 m0, s35, 0xe000
	s_nop 0
	global_load_lds_dwordx4 v150, s[36:37]
	s_waitcnt vmcnt(8)
	s_waitcnt lgkmcnt(0)
	s_barrier
	s_setprio 1
	s_waitcnt lgkmcnt(0)
	v_mfma_f32_16x16x32_bf16 v[124:127], v[128:131], v[178:181], v[124:127]
	v_mfma_f32_16x16x32_bf16 v[120:123], v[136:139], v[178:181], v[120:123]
	v_mfma_f32_16x16x32_bf16 v[116:119], v[128:131], v[186:189], v[116:119]
	v_mfma_f32_16x16x32_bf16 v[108:111], v[136:139], v[186:189], v[108:111]
	v_mfma_f32_16x16x32_bf16 v[96:99], v[128:131], v[194:197], v[96:99]
	v_mfma_f32_16x16x32_bf16 v[88:91], v[136:139], v[194:197], v[88:91]
	v_mfma_f32_16x16x32_bf16 v[84:87], v[128:131], v[202:205], v[84:87]
	v_mfma_f32_16x16x32_bf16 v[76:79], v[136:139], v[202:205], v[76:79]
	v_mfma_f32_16x16x32_bf16 v[124:127], v[132:135], v[182:185], v[124:127]
	v_mfma_f32_16x16x32_bf16 v[120:123], v[140:143], v[182:185], v[120:123]
	v_mfma_f32_16x16x32_bf16 v[116:119], v[132:135], v[190:193], v[116:119]
	v_mfma_f32_16x16x32_bf16 v[108:111], v[140:143], v[190:193], v[108:111]
	v_mfma_f32_16x16x32_bf16 v[96:99], v[132:135], v[198:201], v[96:99]
	v_mfma_f32_16x16x32_bf16 v[88:91], v[140:143], v[198:201], v[88:91]
	v_mfma_f32_16x16x32_bf16 v[84:87], v[132:135], v[206:209], v[84:87]
	v_mfma_f32_16x16x32_bf16 v[76:79], v[140:143], v[206:209], v[76:79]
	s_setprio 0
	s_setprio 1
	v_mfma_f32_16x16x32_bf16 v[112:115], v[156:159], v[178:181], v[112:115]
	v_mfma_f32_16x16x32_bf16 v[104:107], v[170:173], v[178:181], v[104:107]
	v_mfma_f32_16x16x32_bf16 v[100:103], v[156:159], v[186:189], v[100:103]
	v_mfma_f32_16x16x32_bf16 v[92:95], v[170:173], v[186:189], v[92:95]
	v_mfma_f32_16x16x32_bf16 v[80:83], v[156:159], v[194:197], v[80:83]
	v_mfma_f32_16x16x32_bf16 v[72:75], v[170:173], v[194:197], v[72:75]
	v_mfma_f32_16x16x32_bf16 v[68:71], v[156:159], v[202:205], v[68:71]
	v_mfma_f32_16x16x32_bf16 v[64:67], v[170:173], v[202:205], v[64:67]
	v_mfma_f32_16x16x32_bf16 v[112:115], v[166:169], v[182:185], v[112:115]
	v_mfma_f32_16x16x32_bf16 v[104:107], v[174:177], v[182:185], v[104:107]
	v_mfma_f32_16x16x32_bf16 v[100:103], v[166:169], v[190:193], v[100:103]
	v_mfma_f32_16x16x32_bf16 v[92:95], v[174:177], v[190:193], v[92:95]
	v_mfma_f32_16x16x32_bf16 v[80:83], v[166:169], v[198:201], v[80:83]
	v_mfma_f32_16x16x32_bf16 v[72:75], v[174:177], v[198:201], v[72:75]
	v_mfma_f32_16x16x32_bf16 v[68:71], v[166:169], v[206:209], v[68:71]
	v_mfma_f32_16x16x32_bf16 v[64:67], v[174:177], v[206:209], v[64:67]
	s_setprio 0
	s_barrier
	s_add_i32 s64, s55, s46
	s_mov_b32 m0, s64
	ds_read_b128 v[178:181], v165 offset:16384
	ds_read_b128 v[182:185], v165 offset:17408
	ds_read_b128 v[186:189], v165 offset:18432
	ds_read_b128 v[190:193], v165 offset:19456
	ds_read_b128 v[194:197], v165 offset:20480
	ds_read_b128 v[198:201], v165 offset:21504
	ds_read_b128 v[202:205], v165 offset:22528
	ds_read_b128 v[206:209], v165 offset:23552
	global_load_lds_dwordx4 v144, s[38:39]
	s_add_i32 m0, s64, 0x2000
	s_add_u32 s64, s38, 0x40000
	s_addc_u32 s65, s39, 0
	s_add_i32 s66, s56, s46
	global_load_lds_dwordx4 v146, s[38:39]
	s_mov_b32 m0, s66
	s_nop 0
	global_load_lds_dwordx4 v144, s[64:65]
	s_add_i32 m0, s66, 0x2000
	s_nop 0
	global_load_lds_dwordx4 v146, s[64:65]
	s_mov_b32 m0, s35
	s_nop 0
	global_load_lds_dwordx4 v144, s[40:41]
	s_waitcnt vmcnt(7)
	s_waitcnt lgkmcnt(0)
	s_barrier
	s_setprio 1
	s_waitcnt lgkmcnt(0)
	v_mfma_f32_16x16x32_bf16 v[60:63], v[128:131], v[178:181], v[60:63]
	v_mfma_f32_16x16x32_bf16 v[56:59], v[136:139], v[178:181], v[56:59]
	v_mfma_f32_16x16x32_bf16 v[52:55], v[128:131], v[186:189], v[52:55]
	v_mfma_f32_16x16x32_bf16 v[44:47], v[136:139], v[186:189], v[44:47]
	v_mfma_f32_16x16x32_bf16 v[36:39], v[128:131], v[194:197], v[36:39]
	v_mfma_f32_16x16x32_bf16 v[28:31], v[136:139], v[194:197], v[28:31]
	v_mfma_f32_16x16x32_bf16 v[20:23], v[128:131], v[202:205], v[20:23]
	v_mfma_f32_16x16x32_bf16 v[12:15], v[136:139], v[202:205], v[12:15]
	v_mfma_f32_16x16x32_bf16 v[60:63], v[132:135], v[182:185], v[60:63]
	v_mfma_f32_16x16x32_bf16 v[56:59], v[140:143], v[182:185], v[56:59]
	v_mfma_f32_16x16x32_bf16 v[52:55], v[132:135], v[190:193], v[52:55]
	v_mfma_f32_16x16x32_bf16 v[44:47], v[140:143], v[190:193], v[44:47]
	v_mfma_f32_16x16x32_bf16 v[36:39], v[132:135], v[198:201], v[36:39]
	v_mfma_f32_16x16x32_bf16 v[28:31], v[140:143], v[198:201], v[28:31]
	v_mfma_f32_16x16x32_bf16 v[20:23], v[132:135], v[206:209], v[20:23]
	v_mfma_f32_16x16x32_bf16 v[12:15], v[140:143], v[206:209], v[12:15]
	s_setprio 0
	s_setprio 1
	v_mfma_f32_16x16x32_bf16 v[48:51], v[156:159], v[178:181], v[48:51]
	v_mfma_f32_16x16x32_bf16 v[40:43], v[170:173], v[178:181], v[40:43]
	v_mfma_f32_16x16x32_bf16 v[32:35], v[156:159], v[186:189], v[32:35]
	v_mfma_f32_16x16x32_bf16 v[24:27], v[170:173], v[186:189], v[24:27]
	v_mfma_f32_16x16x32_bf16 v[16:19], v[156:159], v[194:197], v[16:19]
	v_mfma_f32_16x16x32_bf16 v[8:11], v[170:173], v[194:197], v[8:11]
	v_mfma_f32_16x16x32_bf16 v[4:7], v[156:159], v[202:205], v[4:7]
	v_mfma_f32_16x16x32_bf16 v[0:3], v[170:173], v[202:205], v[0:3]
	v_mfma_f32_16x16x32_bf16 v[48:51], v[166:169], v[182:185], v[48:51]
	v_mfma_f32_16x16x32_bf16 v[40:43], v[174:177], v[182:185], v[40:43]
	v_mfma_f32_16x16x32_bf16 v[32:35], v[166:169], v[190:193], v[32:35]
	v_mfma_f32_16x16x32_bf16 v[24:27], v[174:177], v[190:193], v[24:27]
	v_mfma_f32_16x16x32_bf16 v[16:19], v[166:169], v[198:201], v[16:19]
	v_mfma_f32_16x16x32_bf16 v[8:11], v[174:177], v[198:201], v[8:11]
	v_mfma_f32_16x16x32_bf16 v[4:7], v[166:169], v[206:209], v[4:7]
	v_mfma_f32_16x16x32_bf16 v[0:3], v[174:177], v[206:209], v[0:3]
	s_setprio 0
	s_barrier
	s_add_i32 s64, 0, 0x18000
	s_add_i32 s65, 0, 0x1c000
	v_add_u32_e32 v140, s64, v161
	v_add_u32_e32 v174, s65, v161
	ds_read_b128 v[128:131], v140
	ds_read_b128 v[132:135], v140 offset:1024
	ds_read_b128 v[136:139], v140 offset:2048
	ds_read_b128 v[140:143], v140 offset:3072
	ds_read_b128 v[156:159], v174
	ds_read_b128 v[166:169], v174 offset:1024
	ds_read_b128 v[170:173], v174 offset:2048
	ds_read_b128 v[174:177], v174 offset:3072
	s_mov_b32 m0, s47
	s_nop 0
	global_load_lds_dwordx4 v146, s[40:41]
	s_add_u32 s40, s40, 0x40000
	s_addc_u32 s41, s41, 0
	s_mov_b32 m0, s48
	ds_read_b128 v[178:181], v165 offset:32768
	ds_read_b128 v[182:185], v165 offset:33792
	ds_read_b128 v[186:189], v165 offset:34816
	ds_read_b128 v[190:193], v165 offset:35840
	ds_read_b128 v[194:197], v165 offset:36864
	ds_read_b128 v[198:201], v165 offset:37888
	ds_read_b128 v[202:205], v165 offset:38912
	ds_read_b128 v[206:209], v165 offset:39936
	global_load_lds_dwordx4 v144, s[40:41]
	s_mov_b32 m0, s49
	s_nop 0
	global_load_lds_dwordx4 v146, s[40:41]
	s_waitcnt vmcnt(8)
	s_waitcnt lgkmcnt(0)
	s_barrier
	s_setprio 1
	s_waitcnt lgkmcnt(0)
	v_mfma_f32_16x16x32_bf16 v[124:127], v[128:131], v[178:181], v[124:127]
	v_mfma_f32_16x16x32_bf16 v[120:123], v[136:139], v[178:181], v[120:123]
	v_mfma_f32_16x16x32_bf16 v[116:119], v[128:131], v[186:189], v[116:119]
	v_mfma_f32_16x16x32_bf16 v[108:111], v[136:139], v[186:189], v[108:111]
	v_mfma_f32_16x16x32_bf16 v[96:99], v[128:131], v[194:197], v[96:99]
	v_mfma_f32_16x16x32_bf16 v[88:91], v[136:139], v[194:197], v[88:91]
	v_mfma_f32_16x16x32_bf16 v[84:87], v[128:131], v[202:205], v[84:87]
	v_mfma_f32_16x16x32_bf16 v[76:79], v[136:139], v[202:205], v[76:79]
	v_mfma_f32_16x16x32_bf16 v[124:127], v[132:135], v[182:185], v[124:127]
	v_mfma_f32_16x16x32_bf16 v[120:123], v[140:143], v[182:185], v[120:123]
	v_mfma_f32_16x16x32_bf16 v[116:119], v[132:135], v[190:193], v[116:119]
	v_mfma_f32_16x16x32_bf16 v[108:111], v[140:143], v[190:193], v[108:111]
	v_mfma_f32_16x16x32_bf16 v[96:99], v[132:135], v[198:201], v[96:99]
	v_mfma_f32_16x16x32_bf16 v[88:91], v[140:143], v[198:201], v[88:91]
	v_mfma_f32_16x16x32_bf16 v[84:87], v[132:135], v[206:209], v[84:87]
	v_mfma_f32_16x16x32_bf16 v[76:79], v[140:143], v[206:209], v[76:79]
	s_setprio 0
	s_setprio 1
	v_mfma_f32_16x16x32_bf16 v[112:115], v[156:159], v[178:181], v[112:115]
	v_mfma_f32_16x16x32_bf16 v[104:107], v[170:173], v[178:181], v[104:107]
	v_mfma_f32_16x16x32_bf16 v[100:103], v[156:159], v[186:189], v[100:103]
	v_mfma_f32_16x16x32_bf16 v[92:95], v[170:173], v[186:189], v[92:95]
	v_mfma_f32_16x16x32_bf16 v[80:83], v[156:159], v[194:197], v[80:83]
	v_mfma_f32_16x16x32_bf16 v[72:75], v[170:173], v[194:197], v[72:75]
	v_mfma_f32_16x16x32_bf16 v[68:71], v[156:159], v[202:205], v[68:71]
	v_mfma_f32_16x16x32_bf16 v[64:67], v[170:173], v[202:205], v[64:67]
	v_mfma_f32_16x16x32_bf16 v[112:115], v[166:169], v[182:185], v[112:115]
	v_mfma_f32_16x16x32_bf16 v[104:107], v[174:177], v[182:185], v[104:107]
	v_mfma_f32_16x16x32_bf16 v[100:103], v[166:169], v[190:193], v[100:103]
	v_mfma_f32_16x16x32_bf16 v[92:95], v[174:177], v[190:193], v[92:95]
	v_mfma_f32_16x16x32_bf16 v[80:83], v[166:169], v[198:201], v[80:83]
	v_mfma_f32_16x16x32_bf16 v[72:75], v[174:177], v[198:201], v[72:75]
	v_mfma_f32_16x16x32_bf16 v[68:71], v[166:169], v[206:209], v[68:71]
	v_mfma_f32_16x16x32_bf16 v[64:67], v[174:177], v[206:209], v[64:67]
	s_setprio 0
	s_barrier
	s_add_i32 s40, s64, s46
	s_mov_b32 m0, s40
	ds_read_b128 v[178:181], v165 offset:49152
	ds_read_b128 v[182:185], v165 offset:50176
	ds_read_b128 v[186:189], v165 offset:51200
	ds_read_b128 v[190:193], v165 offset:52224
	ds_read_b128 v[194:197], v165 offset:53248
	ds_read_b128 v[198:201], v165 offset:54272
	ds_read_b128 v[202:205], v165 offset:55296
	ds_read_b128 v[206:209], v165 offset:56320
	s_add_u32 s38, s38, 0x80
	s_addc_u32 s39, s39, 0
	global_load_lds_dwordx4 v144, s[38:39]
	s_add_i32 m0, s40, 0x2000
	s_add_i32 s40, s65, s46
	global_load_lds_dwordx4 v146, s[38:39]
	s_add_u32 s38, s38, 0x40000
	s_addc_u32 s39, s39, 0
	s_mov_b32 m0, s40
	s_nop 0
	global_load_lds_dwordx4 v144, s[38:39]
	s_add_i32 m0, s40, 0x2000
	s_nop 0
	global_load_lds_dwordx4 v146, s[38:39]
	s_mov_b32 m0, s52
	s_nop 0
	global_load_lds_dwordx4 v144, s[68:69]
	s_waitcnt vmcnt(7)
	s_waitcnt lgkmcnt(0)
	s_barrier
	s_setprio 1
	s_waitcnt lgkmcnt(0)
	v_mfma_f32_16x16x32_bf16 v[60:63], v[128:131], v[178:181], v[60:63]
	v_mfma_f32_16x16x32_bf16 v[56:59], v[136:139], v[178:181], v[56:59]
	v_mfma_f32_16x16x32_bf16 v[52:55], v[128:131], v[186:189], v[52:55]
	v_mfma_f32_16x16x32_bf16 v[44:47], v[136:139], v[186:189], v[44:47]
	v_mfma_f32_16x16x32_bf16 v[36:39], v[128:131], v[194:197], v[36:39]
	v_mfma_f32_16x16x32_bf16 v[28:31], v[136:139], v[194:197], v[28:31]
	v_mfma_f32_16x16x32_bf16 v[20:23], v[128:131], v[202:205], v[20:23]
	v_mfma_f32_16x16x32_bf16 v[12:15], v[136:139], v[202:205], v[12:15]
	v_mfma_f32_16x16x32_bf16 v[60:63], v[132:135], v[182:185], v[60:63]
	v_mfma_f32_16x16x32_bf16 v[56:59], v[140:143], v[182:185], v[56:59]
	v_mfma_f32_16x16x32_bf16 v[52:55], v[132:135], v[190:193], v[52:55]
	v_mfma_f32_16x16x32_bf16 v[44:47], v[140:143], v[190:193], v[44:47]
	v_mfma_f32_16x16x32_bf16 v[36:39], v[132:135], v[198:201], v[36:39]
	v_mfma_f32_16x16x32_bf16 v[28:31], v[140:143], v[198:201], v[28:31]
	v_mfma_f32_16x16x32_bf16 v[20:23], v[132:135], v[206:209], v[20:23]
	v_mfma_f32_16x16x32_bf16 v[12:15], v[140:143], v[206:209], v[12:15]
	s_setprio 0
	s_setprio 1
	v_mfma_f32_16x16x32_bf16 v[48:51], v[156:159], v[178:181], v[48:51]
	v_mfma_f32_16x16x32_bf16 v[40:43], v[170:173], v[178:181], v[40:43]
	v_mfma_f32_16x16x32_bf16 v[32:35], v[156:159], v[186:189], v[32:35]
	v_mfma_f32_16x16x32_bf16 v[24:27], v[170:173], v[186:189], v[24:27]
	v_mfma_f32_16x16x32_bf16 v[16:19], v[156:159], v[194:197], v[16:19]
	s_add_i32 s63, s63, 2
	v_mfma_f32_16x16x32_bf16 v[8:11], v[170:173], v[194:197], v[8:11]
	v_mfma_f32_16x16x32_bf16 v[4:7], v[156:159], v[202:205], v[4:7]
	s_add_u32 s36, s36, 0x100
	s_addc_u32 s37, s37, 0
	v_mfma_f32_16x16x32_bf16 v[0:3], v[170:173], v[202:205], v[0:3]
	v_mfma_f32_16x16x32_bf16 v[48:51], v[166:169], v[182:185], v[48:51]
	s_add_u32 s61, s61, 0x100
	s_addc_u32 s62, s62, 0
	v_mfma_f32_16x16x32_bf16 v[40:43], v[174:177], v[182:185], v[40:43]
	v_mfma_f32_16x16x32_bf16 v[32:35], v[166:169], v[190:193], v[32:35]
	s_cmp_gt_u32 s63, 13
	v_mfma_f32_16x16x32_bf16 v[24:27], v[174:177], v[190:193], v[24:27]
	v_mfma_f32_16x16x32_bf16 v[16:19], v[166:169], v[198:201], v[16:19]
	v_mfma_f32_16x16x32_bf16 v[8:11], v[174:177], v[198:201], v[8:11]
	v_mfma_f32_16x16x32_bf16 v[4:7], v[166:169], v[206:209], v[4:7]
	v_mfma_f32_16x16x32_bf16 v[0:3], v[174:177], v[206:209], v[0:3]
	s_setprio 0
	s_barrier
	s_cbranch_scc0 .LBB0_766
	s_mov_b32 m0, s53
	s_nop 0
	global_load_lds_dwordx4 v146, s[68:69]
	s_and_b64 vcc, exec, s[12:13]
	s_cbranch_vccz .LBB0_769
	s_barrier
